# hand-written FFN norm pass: all row+param loads of an iteration in flight, 16-byte accesses, DPP reductions
# speedup vs baseline: 1.0259x; 1.0100x over previous
.LBB0_1069:
	v_readlane_b32 s0, v242, 7
	v_readlane_b32 s1, v242, 8
	s_and_b64 s[0:1], s[0:1], exec
	s_mov_b32 s0, 0x8800
	s_cselect_b32 s46, s0, 0x8000
	v_readlane_b32 s0, v243, 0
	v_mov_b32_e32 v0, v160
	s_cmp_ge_i32 s0, s46
	v_readlane_b32 s1, v243, 1
	s_cbranch_scc1 .LBB0_1077
	v_lshlrev_b32_e32 v96, 4, v204
	v_lshlrev_b32_e32 v97, 5, v204
	v_readlane_b32 s14, v243, 0
	v_readlane_b32 s15, v242, 9
	v_readlane_b32 s36, v247, 32
	v_readlane_b32 s37, v247, 33
	s_nop 3
	s_lshl_b32 s15, s15, 12
	s_add_u32 s36, s36, s15
	s_addc_u32 s37, s37, 0
	global_load_dwordx4 v[64:67], v97, s[36:37]
	global_load_dwordx4 v[68:71], v97, s[36:37] offset:16
	global_load_dwordx4 v[72:75], v97, s[36:37] offset:2048
	global_load_dwordx4 v[76:79], v97, s[36:37] offset:2064
	s_mov_b32 s26, 0x3a800000
.Lfn_loop:
	s_cmp_lt_u32 s14, 0x8000
	s_cbranch_scc0 .Lfn_ctx
	s_lshl_b32 s38, s14, 11
	s_add_u32 s0, s84, 0xb00000
	s_addc_u32 s1, s85, 0
	s_lshr_b32 s15, s14, 12
	s_branch .Lfn_adr
.Lfn_ctx:
	s_sub_u32 s38, s14, 0x8000
	s_lshl_b32 s38, s38, 11
	s_add_u32 s0, s84, 0x300000
	s_addc_u32 s1, s85, 0
	s_mov_b32 s15, 8
.Lfn_adr:
	s_add_u32 s0, s0, s38
	s_addc_u32 s1, s1, 0
	s_add_u32 s2, s0, 0x1000
	s_addc_u32 s3, s1, 0
	s_lshl_b32 s38, s14, 11
	s_add_u32 s4, s84, 0x4b00000
	s_addc_u32 s5, s85, 0
	s_add_u32 s4, s4, s38
	s_addc_u32 s5, s5, 0
	s_add_u32 s6, s4, 0x1000
	s_addc_u32 s7, s5, 0
	s_mul_i32 s38, s15, 0x6000
	s_add_u32 s12, s30, s38
	s_addc_u32 s13, s31, 0
	s_add_u32 s8, s12, 0x4000
	s_addc_u32 s9, s13, 0
	s_add_u32 s12, s12, 0x3000
	s_addc_u32 s13, s13, 0
	global_load_dwordx4 v[0:3], v96, s[0:1]
	global_load_dwordx4 v[4:7], v96, s[0:1] offset:1024
	global_load_dwordx4 v[8:11], v96, s[0:1] offset:2048
	global_load_dwordx4 v[12:15], v96, s[0:1] offset:3072
	global_load_dwordx4 v[16:19], v96, s[2:3]
	global_load_dwordx4 v[20:23], v96, s[2:3] offset:1024
	global_load_dwordx4 v[24:27], v96, s[2:3] offset:2048
	global_load_dwordx4 v[28:31], v96, s[2:3] offset:3072
	global_load_dwordx4 v[32:35], v97, s[8:9]
	global_load_dwordx4 v[36:39], v97, s[8:9] offset:16
	global_load_dwordx4 v[40:43], v97, s[8:9] offset:2048
	global_load_dwordx4 v[44:47], v97, s[8:9] offset:2064
	global_load_dwordx4 v[48:51], v97, s[12:13]
	global_load_dwordx4 v[52:55], v97, s[12:13] offset:16
	global_load_dwordx4 v[56:59], v97, s[12:13] offset:2048
	global_load_dwordx4 v[60:63], v97, s[12:13] offset:2064
	s_waitcnt vmcnt(8)
	v_lshlrev_b32_e32 v84, 16, v0
	v_and_b32_e32 v85, 0xffff0000, v0
	v_lshlrev_b32_e32 v86, 16, v8
	v_and_b32_e32 v87, 0xffff0000, v8
	v_lshlrev_b32_e32 v88, 16, v16
	v_and_b32_e32 v89, 0xffff0000, v16
	v_lshlrev_b32_e32 v90, 16, v24
	v_and_b32_e32 v91, 0xffff0000, v24
	v_mul_f32_e32 v80, v84, v84
	v_mul_f32_e32 v81, v86, v86
	v_mul_f32_e32 v82, v88, v88
	v_mul_f32_e32 v83, v90, v90
	v_fmac_f32_e32 v80, v85, v85
	v_fmac_f32_e32 v81, v87, v87
	v_fmac_f32_e32 v82, v89, v89
	v_fmac_f32_e32 v83, v91, v91
	v_lshlrev_b32_e32 v84, 16, v1
	v_and_b32_e32 v85, 0xffff0000, v1
	v_lshlrev_b32_e32 v86, 16, v9
	v_and_b32_e32 v87, 0xffff0000, v9
	v_lshlrev_b32_e32 v88, 16, v17
	v_and_b32_e32 v89, 0xffff0000, v17
	v_lshlrev_b32_e32 v90, 16, v25
	v_and_b32_e32 v91, 0xffff0000, v25
	v_fmac_f32_e32 v80, v84, v84
	v_fmac_f32_e32 v81, v86, v86
	v_fmac_f32_e32 v82, v88, v88
	v_fmac_f32_e32 v83, v90, v90
	v_fmac_f32_e32 v80, v85, v85
	v_fmac_f32_e32 v81, v87, v87
	v_fmac_f32_e32 v82, v89, v89
	v_fmac_f32_e32 v83, v91, v91
	v_lshlrev_b32_e32 v84, 16, v2
	v_and_b32_e32 v85, 0xffff0000, v2
	v_lshlrev_b32_e32 v86, 16, v10
	v_and_b32_e32 v87, 0xffff0000, v10
	v_lshlrev_b32_e32 v88, 16, v18
	v_and_b32_e32 v89, 0xffff0000, v18
	v_lshlrev_b32_e32 v90, 16, v26
	v_and_b32_e32 v91, 0xffff0000, v26
	v_fmac_f32_e32 v80, v84, v84
	v_fmac_f32_e32 v81, v86, v86
	v_fmac_f32_e32 v82, v88, v88
	v_fmac_f32_e32 v83, v90, v90
	v_fmac_f32_e32 v80, v85, v85
	v_fmac_f32_e32 v81, v87, v87
	v_fmac_f32_e32 v82, v89, v89
	v_fmac_f32_e32 v83, v91, v91
	v_lshlrev_b32_e32 v84, 16, v3
	v_and_b32_e32 v85, 0xffff0000, v3
	v_lshlrev_b32_e32 v86, 16, v11
	v_and_b32_e32 v87, 0xffff0000, v11
	v_lshlrev_b32_e32 v88, 16, v19
	v_and_b32_e32 v89, 0xffff0000, v19
	v_lshlrev_b32_e32 v90, 16, v27
	v_and_b32_e32 v91, 0xffff0000, v27
	v_fmac_f32_e32 v80, v84, v84
	v_fmac_f32_e32 v81, v86, v86
	v_fmac_f32_e32 v82, v88, v88
	v_fmac_f32_e32 v83, v90, v90
	v_fmac_f32_e32 v80, v85, v85
	v_fmac_f32_e32 v81, v87, v87
	v_fmac_f32_e32 v82, v89, v89
	v_fmac_f32_e32 v83, v91, v91
	v_lshlrev_b32_e32 v84, 16, v4
	v_and_b32_e32 v85, 0xffff0000, v4
	v_lshlrev_b32_e32 v86, 16, v12
	v_and_b32_e32 v87, 0xffff0000, v12
	v_lshlrev_b32_e32 v88, 16, v20
	v_and_b32_e32 v89, 0xffff0000, v20
	v_lshlrev_b32_e32 v90, 16, v28
	v_and_b32_e32 v91, 0xffff0000, v28
	v_fmac_f32_e32 v80, v84, v84
	v_fmac_f32_e32 v81, v86, v86
	v_fmac_f32_e32 v82, v88, v88
	v_fmac_f32_e32 v83, v90, v90
	v_fmac_f32_e32 v80, v85, v85
	v_fmac_f32_e32 v81, v87, v87
	v_fmac_f32_e32 v82, v89, v89
	v_fmac_f32_e32 v83, v91, v91
	v_lshlrev_b32_e32 v84, 16, v5
	v_and_b32_e32 v85, 0xffff0000, v5
	v_lshlrev_b32_e32 v86, 16, v13
	v_and_b32_e32 v87, 0xffff0000, v13
	v_lshlrev_b32_e32 v88, 16, v21
	v_and_b32_e32 v89, 0xffff0000, v21
	v_lshlrev_b32_e32 v90, 16, v29
	v_and_b32_e32 v91, 0xffff0000, v29
	v_fmac_f32_e32 v80, v84, v84
	v_fmac_f32_e32 v81, v86, v86
	v_fmac_f32_e32 v82, v88, v88
	v_fmac_f32_e32 v83, v90, v90
	v_fmac_f32_e32 v80, v85, v85
	v_fmac_f32_e32 v81, v87, v87
	v_fmac_f32_e32 v82, v89, v89
	v_fmac_f32_e32 v83, v91, v91
	v_lshlrev_b32_e32 v84, 16, v6
	v_and_b32_e32 v85, 0xffff0000, v6
	v_lshlrev_b32_e32 v86, 16, v14
	v_and_b32_e32 v87, 0xffff0000, v14
	v_lshlrev_b32_e32 v88, 16, v22
	v_and_b32_e32 v89, 0xffff0000, v22
	v_lshlrev_b32_e32 v90, 16, v30
	v_and_b32_e32 v91, 0xffff0000, v30
	v_fmac_f32_e32 v80, v84, v84
	v_fmac_f32_e32 v81, v86, v86
	v_fmac_f32_e32 v82, v88, v88
	v_fmac_f32_e32 v83, v90, v90
	v_fmac_f32_e32 v80, v85, v85
	v_fmac_f32_e32 v81, v87, v87
	v_fmac_f32_e32 v82, v89, v89
	v_fmac_f32_e32 v83, v91, v91
	v_lshlrev_b32_e32 v84, 16, v7
	v_and_b32_e32 v85, 0xffff0000, v7
	v_lshlrev_b32_e32 v86, 16, v15
	v_and_b32_e32 v87, 0xffff0000, v15
	v_lshlrev_b32_e32 v88, 16, v23
	v_and_b32_e32 v89, 0xffff0000, v23
	v_lshlrev_b32_e32 v90, 16, v31
	v_and_b32_e32 v91, 0xffff0000, v31
	v_fmac_f32_e32 v80, v84, v84
	v_fmac_f32_e32 v81, v86, v86
	v_fmac_f32_e32 v82, v88, v88
	v_fmac_f32_e32 v83, v90, v90
	v_fmac_f32_e32 v80, v85, v85
	v_fmac_f32_e32 v81, v87, v87
	v_fmac_f32_e32 v82, v89, v89
	v_fmac_f32_e32 v83, v91, v91
	v_add_f32_dpp v80, v80, v80 quad_perm:[1,0,3,2] row_mask:0xf bank_mask:0xf
	v_add_f32_dpp v81, v81, v81 quad_perm:[1,0,3,2] row_mask:0xf bank_mask:0xf
	v_add_f32_dpp v82, v82, v82 quad_perm:[1,0,3,2] row_mask:0xf bank_mask:0xf
	v_add_f32_dpp v83, v83, v83 quad_perm:[1,0,3,2] row_mask:0xf bank_mask:0xf
	s_nop 0
	v_add_f32_dpp v80, v80, v80 quad_perm:[2,3,0,1] row_mask:0xf bank_mask:0xf
	v_add_f32_dpp v81, v81, v81 quad_perm:[2,3,0,1] row_mask:0xf bank_mask:0xf
	v_add_f32_dpp v82, v82, v82 quad_perm:[2,3,0,1] row_mask:0xf bank_mask:0xf
	v_add_f32_dpp v83, v83, v83 quad_perm:[2,3,0,1] row_mask:0xf bank_mask:0xf
	s_nop 0
	v_add_f32_dpp v80, v80, v80 row_half_mirror row_mask:0xf bank_mask:0xf
	v_add_f32_dpp v81, v81, v81 row_half_mirror row_mask:0xf bank_mask:0xf
	v_add_f32_dpp v82, v82, v82 row_half_mirror row_mask:0xf bank_mask:0xf
	v_add_f32_dpp v83, v83, v83 row_half_mirror row_mask:0xf bank_mask:0xf
	s_nop 0
	v_add_f32_dpp v80, v80, v80 row_mirror row_mask:0xf bank_mask:0xf
	v_add_f32_dpp v81, v81, v81 row_mirror row_mask:0xf bank_mask:0xf
	v_add_f32_dpp v82, v82, v82 row_mirror row_mask:0xf bank_mask:0xf
	v_add_f32_dpp v83, v83, v83 row_mirror row_mask:0xf bank_mask:0xf
	s_nop 0
	v_add_f32_dpp v80, v80, v80 row_bcast:15 row_mask:0xa bank_mask:0xf
	v_add_f32_dpp v81, v81, v81 row_bcast:15 row_mask:0xa bank_mask:0xf
	v_add_f32_dpp v82, v82, v82 row_bcast:15 row_mask:0xa bank_mask:0xf
	v_add_f32_dpp v83, v83, v83 row_bcast:15 row_mask:0xa bank_mask:0xf
	s_nop 0
	v_add_f32_dpp v80, v80, v80 row_bcast:31 row_mask:0xc bank_mask:0xf
	v_add_f32_dpp v81, v81, v81 row_bcast:31 row_mask:0xc bank_mask:0xf
	v_add_f32_dpp v82, v82, v82 row_bcast:31 row_mask:0xc bank_mask:0xf
	v_add_f32_dpp v83, v83, v83 row_bcast:31 row_mask:0xc bank_mask:0xf
	s_nop 0
	v_mov_b32_e32 v92, 0x358637bd
	s_nop 0
	v_fma_f32 v80, v80, s26, v92
	v_fma_f32 v81, v81, s26, v92
	v_fma_f32 v82, v82, s26, v92
	v_fma_f32 v83, v83, s26, v92
	v_rsq_f32_e32 v80, v80
	v_rsq_f32_e32 v81, v81
	v_rsq_f32_e32 v82, v82
	v_rsq_f32_e32 v83, v83
	s_nop 1
	v_readlane_b32 s16, v80, 63
	v_readlane_b32 s17, v81, 63
	v_readlane_b32 s18, v82, 63
	v_readlane_b32 s19, v83, 63
	s_waitcnt vmcnt(0)
	v_add_f32_e32 v32, 1.0, v32
	v_add_f32_e32 v33, 1.0, v33
	v_add_f32_e32 v34, 1.0, v34
	v_add_f32_e32 v35, 1.0, v35
	v_add_f32_e32 v36, 1.0, v36
	v_add_f32_e32 v37, 1.0, v37
	v_add_f32_e32 v38, 1.0, v38
	v_add_f32_e32 v39, 1.0, v39
	v_add_f32_e32 v40, 1.0, v40
	v_add_f32_e32 v41, 1.0, v41
	v_add_f32_e32 v42, 1.0, v42
	v_add_f32_e32 v43, 1.0, v43
	v_add_f32_e32 v44, 1.0, v44
	v_add_f32_e32 v45, 1.0, v45
	v_add_f32_e32 v46, 1.0, v46
	v_add_f32_e32 v47, 1.0, v47
	v_mul_f32_e32 v32, v64, v32
	v_mul_f32_e32 v33, v65, v33
	v_mul_f32_e32 v34, v66, v34
	v_mul_f32_e32 v35, v67, v35
	v_mul_f32_e32 v36, v68, v36
	v_mul_f32_e32 v37, v69, v37
	v_mul_f32_e32 v38, v70, v38
	v_mul_f32_e32 v39, v71, v39
	v_mul_f32_e32 v40, v72, v40
	v_mul_f32_e32 v41, v73, v41
	v_mul_f32_e32 v42, v74, v42
	v_mul_f32_e32 v43, v75, v43
	v_mul_f32_e32 v44, v76, v44
	v_mul_f32_e32 v45, v77, v45
	v_mul_f32_e32 v46, v78, v46
	v_mul_f32_e32 v47, v79, v47
	v_lshlrev_b32_e32 v84, 16, v0
	v_and_b32_e32 v85, 0xffff0000, v0
	v_mul_f32_e32 v84, s16, v84
	v_mul_f32_e32 v85, s16, v85
	v_fma_f32 v84, v84, v32, v48
	v_fma_f32 v85, v85, v33, v49
	v_cvt_pk_bf16_f32 v0, v84, v85
	v_lshlrev_b32_e32 v86, 16, v1
	v_and_b32_e32 v87, 0xffff0000, v1
	v_mul_f32_e32 v86, s16, v86
	v_mul_f32_e32 v87, s16, v87
	v_fma_f32 v86, v86, v34, v50
	v_fma_f32 v87, v87, v35, v51
	v_cvt_pk_bf16_f32 v1, v86, v87
	v_lshlrev_b32_e32 v88, 16, v2
	v_and_b32_e32 v89, 0xffff0000, v2
	v_mul_f32_e32 v88, s16, v88
	v_mul_f32_e32 v89, s16, v89
	v_fma_f32 v88, v88, v36, v52
	v_fma_f32 v89, v89, v37, v53
	v_cvt_pk_bf16_f32 v2, v88, v89
	v_lshlrev_b32_e32 v90, 16, v3
	v_and_b32_e32 v91, 0xffff0000, v3
	v_mul_f32_e32 v90, s16, v90
	v_mul_f32_e32 v91, s16, v91
	v_fma_f32 v90, v90, v38, v54
	v_fma_f32 v91, v91, v39, v55
	v_cvt_pk_bf16_f32 v3, v90, v91
	global_store_dwordx4 v96, v[0:3], s[4:5]
	v_lshlrev_b32_e32 v84, 16, v4
	v_and_b32_e32 v85, 0xffff0000, v4
	v_mul_f32_e32 v84, s16, v84
	v_mul_f32_e32 v85, s16, v85
	v_fma_f32 v84, v84, v40, v56
	v_fma_f32 v85, v85, v41, v57
	v_cvt_pk_bf16_f32 v4, v84, v85
	v_lshlrev_b32_e32 v86, 16, v5
	v_and_b32_e32 v87, 0xffff0000, v5
	v_mul_f32_e32 v86, s16, v86
	v_mul_f32_e32 v87, s16, v87
	v_fma_f32 v86, v86, v42, v58
	v_fma_f32 v87, v87, v43, v59
	v_cvt_pk_bf16_f32 v5, v86, v87
	v_lshlrev_b32_e32 v88, 16, v6
	v_and_b32_e32 v89, 0xffff0000, v6
	v_mul_f32_e32 v88, s16, v88
	v_mul_f32_e32 v89, s16, v89
	v_fma_f32 v88, v88, v44, v60
	v_fma_f32 v89, v89, v45, v61
	v_cvt_pk_bf16_f32 v6, v88, v89
	v_lshlrev_b32_e32 v90, 16, v7
	v_and_b32_e32 v91, 0xffff0000, v7
	v_mul_f32_e32 v90, s16, v90
	v_mul_f32_e32 v91, s16, v91
	v_fma_f32 v90, v90, v46, v62
	v_fma_f32 v91, v91, v47, v63
	v_cvt_pk_bf16_f32 v7, v90, v91
	global_store_dwordx4 v96, v[4:7], s[4:5] offset:1024
	v_lshlrev_b32_e32 v84, 16, v8
	v_and_b32_e32 v85, 0xffff0000, v8
	v_mul_f32_e32 v84, s17, v84
	v_mul_f32_e32 v85, s17, v85
	v_fma_f32 v84, v84, v32, v48
	v_fma_f32 v85, v85, v33, v49
	v_cvt_pk_bf16_f32 v8, v84, v85
	v_lshlrev_b32_e32 v86, 16, v9
	v_and_b32_e32 v87, 0xffff0000, v9
	v_mul_f32_e32 v86, s17, v86
	v_mul_f32_e32 v87, s17, v87
	v_fma_f32 v86, v86, v34, v50
	v_fma_f32 v87, v87, v35, v51
	v_cvt_pk_bf16_f32 v9, v86, v87
	v_lshlrev_b32_e32 v88, 16, v10
	v_and_b32_e32 v89, 0xffff0000, v10
	v_mul_f32_e32 v88, s17, v88
	v_mul_f32_e32 v89, s17, v89
	v_fma_f32 v88, v88, v36, v52
	v_fma_f32 v89, v89, v37, v53
	v_cvt_pk_bf16_f32 v10, v88, v89
	v_lshlrev_b32_e32 v90, 16, v11
	v_and_b32_e32 v91, 0xffff0000, v11
	v_mul_f32_e32 v90, s17, v90
	v_mul_f32_e32 v91, s17, v91
	v_fma_f32 v90, v90, v38, v54
	v_fma_f32 v91, v91, v39, v55
	v_cvt_pk_bf16_f32 v11, v90, v91
	global_store_dwordx4 v96, v[8:11], s[4:5] offset:2048
	v_lshlrev_b32_e32 v84, 16, v12
	v_and_b32_e32 v85, 0xffff0000, v12
	v_mul_f32_e32 v84, s17, v84
	v_mul_f32_e32 v85, s17, v85
	v_fma_f32 v84, v84, v40, v56
	v_fma_f32 v85, v85, v41, v57
	v_cvt_pk_bf16_f32 v12, v84, v85
	v_lshlrev_b32_e32 v86, 16, v13
	v_and_b32_e32 v87, 0xffff0000, v13
	v_mul_f32_e32 v86, s17, v86
	v_mul_f32_e32 v87, s17, v87
	v_fma_f32 v86, v86, v42, v58
	v_fma_f32 v87, v87, v43, v59
	v_cvt_pk_bf16_f32 v13, v86, v87
	v_lshlrev_b32_e32 v88, 16, v14
	v_and_b32_e32 v89, 0xffff0000, v14
	v_mul_f32_e32 v88, s17, v88
	v_mul_f32_e32 v89, s17, v89
	v_fma_f32 v88, v88, v44, v60
	v_fma_f32 v89, v89, v45, v61
	v_cvt_pk_bf16_f32 v14, v88, v89
	v_lshlrev_b32_e32 v90, 16, v15
	v_and_b32_e32 v91, 0xffff0000, v15
	v_mul_f32_e32 v90, s17, v90
	v_mul_f32_e32 v91, s17, v91
	v_fma_f32 v90, v90, v46, v62
	v_fma_f32 v91, v91, v47, v63
	v_cvt_pk_bf16_f32 v15, v90, v91
	global_store_dwordx4 v96, v[12:15], s[4:5] offset:3072
	v_lshlrev_b32_e32 v84, 16, v16
	v_and_b32_e32 v85, 0xffff0000, v16
	v_mul_f32_e32 v84, s18, v84
	v_mul_f32_e32 v85, s18, v85
	v_fma_f32 v84, v84, v32, v48
	v_fma_f32 v85, v85, v33, v49
	v_cvt_pk_bf16_f32 v16, v84, v85
	v_lshlrev_b32_e32 v86, 16, v17
	v_and_b32_e32 v87, 0xffff0000, v17
	v_mul_f32_e32 v86, s18, v86
	v_mul_f32_e32 v87, s18, v87
	v_fma_f32 v86, v86, v34, v50
	v_fma_f32 v87, v87, v35, v51
	v_cvt_pk_bf16_f32 v17, v86, v87
	v_lshlrev_b32_e32 v88, 16, v18
	v_and_b32_e32 v89, 0xffff0000, v18
	v_mul_f32_e32 v88, s18, v88
	v_mul_f32_e32 v89, s18, v89
	v_fma_f32 v88, v88, v36, v52
	v_fma_f32 v89, v89, v37, v53
	v_cvt_pk_bf16_f32 v18, v88, v89
	v_lshlrev_b32_e32 v90, 16, v19
	v_and_b32_e32 v91, 0xffff0000, v19
	v_mul_f32_e32 v90, s18, v90
	v_mul_f32_e32 v91, s18, v91
	v_fma_f32 v90, v90, v38, v54
	v_fma_f32 v91, v91, v39, v55
	v_cvt_pk_bf16_f32 v19, v90, v91
	global_store_dwordx4 v96, v[16:19], s[6:7]
	v_lshlrev_b32_e32 v84, 16, v20
	v_and_b32_e32 v85, 0xffff0000, v20
	v_mul_f32_e32 v84, s18, v84
	v_mul_f32_e32 v85, s18, v85
	v_fma_f32 v84, v84, v40, v56
	v_fma_f32 v85, v85, v41, v57
	v_cvt_pk_bf16_f32 v20, v84, v85
	v_lshlrev_b32_e32 v86, 16, v21
	v_and_b32_e32 v87, 0xffff0000, v21
	v_mul_f32_e32 v86, s18, v86
	v_mul_f32_e32 v87, s18, v87
	v_fma_f32 v86, v86, v42, v58
	v_fma_f32 v87, v87, v43, v59
	v_cvt_pk_bf16_f32 v21, v86, v87
	v_lshlrev_b32_e32 v88, 16, v22
	v_and_b32_e32 v89, 0xffff0000, v22
	v_mul_f32_e32 v88, s18, v88
	v_mul_f32_e32 v89, s18, v89
	v_fma_f32 v88, v88, v44, v60
	v_fma_f32 v89, v89, v45, v61
	v_cvt_pk_bf16_f32 v22, v88, v89
	v_lshlrev_b32_e32 v90, 16, v23
	v_and_b32_e32 v91, 0xffff0000, v23
	v_mul_f32_e32 v90, s18, v90
	v_mul_f32_e32 v91, s18, v91
	v_fma_f32 v90, v90, v46, v62
	v_fma_f32 v91, v91, v47, v63
	v_cvt_pk_bf16_f32 v23, v90, v91
	global_store_dwordx4 v96, v[20:23], s[6:7] offset:1024
	v_lshlrev_b32_e32 v84, 16, v24
	v_and_b32_e32 v85, 0xffff0000, v24
	v_mul_f32_e32 v84, s19, v84
	v_mul_f32_e32 v85, s19, v85
	v_fma_f32 v84, v84, v32, v48
	v_fma_f32 v85, v85, v33, v49
	v_cvt_pk_bf16_f32 v24, v84, v85
	v_lshlrev_b32_e32 v86, 16, v25
	v_and_b32_e32 v87, 0xffff0000, v25
	v_mul_f32_e32 v86, s19, v86
	v_mul_f32_e32 v87, s19, v87
	v_fma_f32 v86, v86, v34, v50
	v_fma_f32 v87, v87, v35, v51
	v_cvt_pk_bf16_f32 v25, v86, v87
	v_lshlrev_b32_e32 v88, 16, v26
	v_and_b32_e32 v89, 0xffff0000, v26
	v_mul_f32_e32 v88, s19, v88
	v_mul_f32_e32 v89, s19, v89
	v_fma_f32 v88, v88, v36, v52
	v_fma_f32 v89, v89, v37, v53
	v_cvt_pk_bf16_f32 v26, v88, v89
	v_lshlrev_b32_e32 v90, 16, v27
	v_and_b32_e32 v91, 0xffff0000, v27
	v_mul_f32_e32 v90, s19, v90
	v_mul_f32_e32 v91, s19, v91
	v_fma_f32 v90, v90, v38, v54
	v_fma_f32 v91, v91, v39, v55
	v_cvt_pk_bf16_f32 v27, v90, v91
	global_store_dwordx4 v96, v[24:27], s[6:7] offset:2048
	v_lshlrev_b32_e32 v84, 16, v28
	v_and_b32_e32 v85, 0xffff0000, v28
	v_mul_f32_e32 v84, s19, v84
	v_mul_f32_e32 v85, s19, v85
	v_fma_f32 v84, v84, v40, v56
	v_fma_f32 v85, v85, v41, v57
	v_cvt_pk_bf16_f32 v28, v84, v85
	v_lshlrev_b32_e32 v86, 16, v29
	v_and_b32_e32 v87, 0xffff0000, v29
	v_mul_f32_e32 v86, s19, v86
	v_mul_f32_e32 v87, s19, v87
	v_fma_f32 v86, v86, v42, v58
	v_fma_f32 v87, v87, v43, v59
	v_cvt_pk_bf16_f32 v29, v86, v87
	v_lshlrev_b32_e32 v88, 16, v30
	v_and_b32_e32 v89, 0xffff0000, v30
	v_mul_f32_e32 v88, s19, v88
	v_mul_f32_e32 v89, s19, v89
	v_fma_f32 v88, v88, v44, v60
	v_fma_f32 v89, v89, v45, v61
	v_cvt_pk_bf16_f32 v30, v88, v89
	v_lshlrev_b32_e32 v90, 16, v31
	v_and_b32_e32 v91, 0xffff0000, v31
	v_mul_f32_e32 v90, s19, v90
	v_mul_f32_e32 v91, s19, v91
	v_fma_f32 v90, v90, v46, v62
	v_fma_f32 v91, v91, v47, v63
	v_cvt_pk_bf16_f32 v31, v90, v91
	global_store_dwordx4 v96, v[28:31], s[6:7] offset:3072
	s_add_u32 s14, s14, s24
	s_cmp_lt_u32 s14, s46
	s_cbranch_scc1 .Lfn_loop
